# rev3
# speedup vs baseline: 1.0048x; 1.0048x over previous
; template <int EPI> ...
;     ...
;   int wid = tid >> 6, lane = tid & 63, wr = wid >> 2, wc = wid & 3, fr = lane & 15, fq = lane >> 4;
;   f32x4 acc[2][2][4][2] = {};
;   bf16x8 At[4][2], B0[2][2], B1[2][2];
;   int nt = K / BK;
;   const int aoff0 = lds_byte(wr * 64 + fr, fq * 8), aoff1 = lds_byte(wr * 64 + fr, 32 + fq * 8);
;   const int brw = wc * 32 + (fr >> 2) * 8 + (fr & 3);
;   const int boff0 = lds_byte(brw, fq * 8), boff1 = lds_byte(brw, 32 + fq * 8);
;   unsigned loff0;
;   { int _r, _c; stage_rc(tid * 16, _r, _c); loff0 = (unsigned)(_r * K + _c) * 2u; }
; template <int EPI>
; __device__ __forceinline__ void gemm_phase(const u16* A, const u16* Bt, int M, int N, int K, u16* out, int ldo,
;                                            const float* aux, int bid, int nblk, int wv) {
;   int nM = M / BM, nN = N / BM, ntile = nM * nN;
;   int tid = opaque_tid(wv);
;   for (int base = 0; base < ntile; base += nblk) {
;     int wgid;
;     if (base + nblk <= ntile && (nblk & 7) == 0) wgid = base + (bid & 7) * (nblk >> 3) + (bid >> 3);
.LBB0_270:
	s_or_b64 exec, exec, s[2:3]
	s_mov_b64 s[2:3], s[0:1]
	s_barrier
	s_load_dwordx2 s[6:7], s[2:3], 0xe0
	v_mbcnt_lo_u32_b32 v0, -1, 0
	v_mbcnt_hi_u32_b32 v0, -1, v0
	s_movk_i32 s4, 0xff
	v_or_b32_e32 v1, s15, v0
	v_lshrrev_b32_e32 v2, 2, v1
	s_waitcnt lgkmcnt(0)
	s_add_u32 s14, s6, 0xaaf0000
	s_addc_u32 s43, s7, 0
	s_add_u32 s8, s6, 0x12af0000
	s_addc_u32 s9, s7, 0
	s_and_b32 s2, s33, 7
	s_cmp_eq_u32 s2, 0
	s_cselect_b64 s[44:45], -1, 0
	s_and_b32 s80, s91, 7
	s_ashr_i32 s2, s33, 3
	s_mul_i32 s86, s2, s80
	s_ashr_i32 s2, s91, 3
	s_add_i32 s86, s86, s2
	v_and_b32_e32 v2, 64, v2
	v_lshlrev_b32_e32 v4, 6, v1
	v_and_b32_e32 v5, 48, v0
	s_movk_i32 s2, 0x3c0
	v_lshlrev_b32_e32 v7, 2, v1
	v_and_or_b32 v4, v4, s2, v5
	v_lshlrev_b32_e32 v6, 7, v2
	v_and_b32_e32 v7, 32, v7
	v_bitop3_b32 v4, v4, v6, v7 bitop3:0xde
	v_lshlrev_b32_e32 v6, 1, v1
	v_and_b32_e32 v6, 24, v6
	v_and_or_b32 v7, v0, 3, v6
	v_lshrrev_b32_e32 v3, 1, v1
	s_movk_i32 s2, 0x60
	v_lshlrev_b32_e32 v7, 6, v7
	v_lshlrev_b32_e32 v8, 3, v1
	v_and_or_b32 v6, v3, s2, v6
	v_and_b32_e32 v7, 0x2c0, v7
	v_and_b32_e32 v8, 32, v8
	v_lshlrev_b32_e32 v6, 7, v6
	v_bitop3_b32 v5, v7, v8, v5 bitop3:0x36
	s_movk_i32 s2, 0x3800
	v_and_or_b32 v7, v6, s2, v5
	s_movk_i32 s2, 0x400
	v_or3_b32 v5, v6, v5, s2
	v_lshlrev_b32_e32 v6, 4, v1
	v_and_b32_e32 v8, 32, v0
	v_lshrrev_b32_e32 v9, 3, v1
	v_bfe_u32 v10, v1, 2, 4
	v_bitop3_b32 v8, v6, v8, 48 bitop3:0x6c
	v_bitop3_b32 v11, v0, 64, s15 bitop3:0xc8
	s_movk_i32 s2, 0x100
	v_and_or_b32 v134, v0, 15, v2
	v_lshlrev_b32_e32 v0, 9, v1
	s_mov_b32 s10, 0x30000
	s_add_i32 s87, 0, 0x10000
	s_add_i32 s88, 0, 0x14000
	s_add_i32 s89, 0, 0x18000
	s_add_i32 s90, 0, 0x1c000
	v_and_or_b32 v9, v9, 48, v10
	v_or_b32_e32 v12, v11, v8
	v_mov_b32_e32 v129, 0
	v_cmp_gt_u32_e64 s[2:3], s2, v1
	v_cmp_lt_u32_e64 s[4:5], s4, v1
	v_and_or_b32 v0, v0, s10, v8
	v_lshlrev_b32_e32 v1, 12, v10
	v_add_u32_e32 v136, s87, v6
	v_add_u32_e32 v138, 0, v6
	v_add_u32_e32 v140, s88, v6
	v_add_u32_e32 v144, s89, v6
	v_add_u32_e32 v148, s90, v6
	s_mov_b32 s74, 0
	v_lshl_or_b32 v128, v9, 12, v12
	v_and_b32_e32 v135, 0x78, v3
	v_or3_b32 v130, v0, v1, v11
	v_mov_b32_e32 v131, v129
	s_mov_b64 s[10:11], 0x40000
	v_add_u32_e32 v137, 0x2000, v136
	v_add_u32_e32 v139, 0x2000, v138
	v_add_u32_e32 v141, 0x2000, v140
	v_add_u32_e32 v142, 0x4000, v138
	v_add_u32_e32 v143, 0x6000, v138
	s_mov_b64 s[12:13], 0x80
	s_mov_b64 s[16:17], 0x40080
	v_add_u32_e32 v145, 0x2000, v144
	v_add_u32_e32 v146, 0x8000, v138
	v_add_u32_e32 v147, 0xa000, v138
	v_add_u32_e32 v149, 0x2000, v148
	v_add_u32_e32 v150, 0, v4
	s_mov_b64 s[18:19], 0xab70080
	v_add_u32_e32 v151, 0xc000, v138
	s_mov_b64 s[20:21], 0xabb0080
	v_add_u32_e32 v152, 0xe000, v138
	s_mov_b64 s[22:23], 0x100
	s_mov_b64 s[26:27], 0x40100
	s_mov_b64 s[28:29], 0xaaf0100
	s_mov_b64 s[30:31], 0xab30100
	s_mov_b64 s[36:37], 0x80100
	s_mov_b64 s[38:39], 0xc0100
	s_mov_b64 s[46:47], 0xab70100
	s_mov_b64 s[48:49], 0xabb0100
	s_mov_b64 s[50:51], 0x180
	s_mov_b64 s[52:53], 0x40180
	s_mov_b64 s[54:55], 0xaaf0180
	s_mov_b64 s[56:57], 0xab30180
	s_mov_b64 s[58:59], 0x80180
	s_mov_b64 s[60:61], 0xc0180
	s_mov_b64 s[62:63], 0xf80
	s_mov_b64 s[64:65], 0x40f80
	s_movk_i32 s75, 0x2c00
	v_add_u32_e32 v153, s87, v7
	v_add_u32_e32 v154, s87, v5
	v_add_u32_e32 v155, s88, v7
	v_add_u32_e32 v156, s88, v5
	v_add_u32_e32 v157, s89, v7
	v_add_u32_e32 v158, s89, v5
	v_add_u32_e32 v159, s90, v7
	v_add_u32_e32 v160, s90, v5
	s_branch .LBB0_273

; #define STAGE(P, BASE, br, kt) do { const char* _gb = (const char*)(BASE) + ((size_t)(br) * K + (size_t)(kt) * BK) * 2; \
;     __builtin_amdgcn_global_load_lds((const unsigned*)(_gb + loff0), (unsigned*)((char*)(P) + tid * 16), 16, 0, 0); \
;     __builtin_amdgcn_global_load_lds((const unsigned*)(_gb + (size_t)K * 128 + loff0), (unsigned*)((char*)(P) + tid * 16 + 8192), 16, 0, 0); } while (0)
; #define WAIT_V(n) asm volatile("s_waitcnt vmcnt(" #n ")" ::: "memory")
; #define BAR __builtin_amdgcn_s_barrier()
; template <int EPI> ...
;     ...
;   STAGE(SB(0, 0), Bt, bcol, 0); STAGE(SA(0, 0), A, brow, 0);
;   STAGE(SB(0, 1), Bt, bcol + HALF, 0); STAGE(SA(0, 1), A, brow + HALF, 0);
;   if (wr == 1) BAR;
;   WAIT_V(4); BAR;
;   STAGE(SB(1, 0), Bt, bcol, 1); STAGE(SA(1, 0), A, brow, 1); STAGE(SB(1, 1), Bt, bcol + HALF, 1);
;   WAIT_V(6); BAR;
; template <int EPI>
; __device__ __forceinline__ void gemm_phase(const u16* A, const u16* Bt, int M, int N, int K, u16* out, int ldo,
;                                            const float* aux, int bid, int nblk, int wv) {
;     ...
;   for (int base = 0; base < ntile; base += nblk) {
;     int wgid;
;     if (base + nblk <= ntile && (nblk & 7) == 0) wgid = base + (bid & 7) * (nblk >> 3) + (bid >> 3);
;     else wgid = base + bid;
;     if (wgid >= ntile) break;
;     int nig = WGM * nN, gid = wgid / nig, fm = gid * WGM, gsz = min(nM - fm, WGM);
;     int pm = fm + ((wgid % nig) % gsz), pn = (wgid % nig) / gsz;
;     int brow = pm * BM, bcol = pn * BM;
.LBB0_272:
	s_and_b64 vcc, exec, s[66:67]
	s_cbranch_vccnz .LBB0_280
.LBB0_273:
	s_mov_b32 s68, s74
	s_add_i32 s74, s74, s33
	s_cmpk_lt_i32 s74, 0x1601
	s_cselect_b64 s[66:67], -1, 0
	s_and_b64 s[66:67], s[44:45], s[66:67]
	s_and_b64 s[66:67], s[66:67], exec
	s_cselect_b32 s66, s86, s91
	s_add_i32 s68, s66, s68
	s_cmpk_gt_i32 s68, 0x15ff
	s_mov_b64 s[66:67], -1
	s_cbranch_scc1 .LBB0_272
	s_mul_hi_i32 s66, s68, 0x2e8ba2e9
	s_lshr_b32 s67, s66, 31
	s_ashr_i32 s66, s66, 6
	s_add_i32 s66, s66, s67
	s_mul_i32 s67, s66, 0x160
	s_sub_i32 s67, s68, s67
	s_sext_i32_i16 s68, s67
	s_bfe_u32 s68, s68, 0x3001c
	s_add_i32 s68, s67, s68
	s_sext_i32_i16 s69, s68
	s_and_b32 s68, s68, 0xfff8
	s_sub_i32 s67, s67, s68
	s_ashr_i32 s76, s69, 3
	s_sext_i32_i16 s67, s67
	s_lshl_b32 s72, s76, 8
	s_lshl_b32 s66, s66, 11
	s_lshl_b32 s67, s67, 8
	s_ashr_i32 s73, s72, 31
	s_add_i32 s66, s67, s66
	s_lshl_b64 s[68:69], s[72:73], 12
	s_add_u32 s68, s6, s68
	s_addc_u32 s69, s7, s69
	v_readfirstlane_b32 s67, v136
	v_lshl_add_u64 v[0:1], s[68:69], 0, v[128:129]
	s_mov_b32 m0, s67
	v_readfirstlane_b32 s67, v137
	global_load_lds_dwordx4 v[0:1], off
	s_mov_b32 m0, s67
	s_ashr_i32 s67, s66, 31
	s_lshl_b64 s[70:71], s[66:67], 12
	s_add_u32 s78, s14, s70
	s_addc_u32 s79, s43, s71
	s_bitset1_b32 s72, 7
	s_ashr_i32 s73, s72, 31
	v_lshl_add_u64 v[2:3], v[0:1], 0, s[10:11]
	v_readfirstlane_b32 s67, v138
	s_lshl_b64 s[72:73], s[72:73], 12
	global_load_lds_dwordx4 v[2:3], off
	v_lshl_add_u64 v[2:3], s[78:79], 0, v[128:129]
	s_mov_b32 m0, s67
	v_readfirstlane_b32 s67, v139
	s_add_u32 s72, s6, s72
	global_load_lds_dwordx4 v[2:3], off
	v_lshl_add_u64 v[4:5], v[2:3], 0, s[10:11]
	s_mov_b32 m0, s67
	s_addc_u32 s73, s7, s73
	global_load_lds_dwordx4 v[4:5], off
	v_lshl_add_u64 v[4:5], s[72:73], 0, v[128:129]
	s_or_b32 s72, s66, 0x80
	s_ashr_i32 s73, s72, 31
	v_readfirstlane_b32 s67, v140
	s_lshl_b64 s[72:73], s[72:73], 12
	s_mov_b32 m0, s67
	v_readfirstlane_b32 s67, v141
	s_add_u32 s72, s14, s72
	global_load_lds_dwordx4 v[4:5], off
	v_lshl_add_u64 v[6:7], v[4:5], 0, s[10:11]
	s_mov_b32 m0, s67
	s_addc_u32 s73, s43, s73
	v_readfirstlane_b32 s67, v142
	global_load_lds_dwordx4 v[6:7], off
	v_lshl_add_u64 v[132:133], s[72:73], 0, v[128:129]
	s_mov_b32 m0, s67
	v_readfirstlane_b32 s67, v143
	global_load_lds_dwordx4 v[132:133], off
	v_lshl_add_u64 v[6:7], v[132:133], 0, s[10:11]
	s_mov_b32 m0, s67
	s_nop 0
	global_load_lds_dwordx4 v[6:7], off
	s_and_saveexec_b64 s[72:73], s[4:5]
	s_cbranch_execz .LBB0_276
	s_barrier
.LBB0_276:
	s_or_b64 exec, exec, s[72:73]
	v_readfirstlane_b32 s67, v144
	v_lshl_add_u64 v[6:7], v[0:1], 0, s[12:13]
	s_mov_b32 m0, s67
	v_readfirstlane_b32 s67, v145
	s_waitcnt vmcnt(4)
	s_barrier
	global_load_lds_dwordx4 v[6:7], off
	v_lshl_add_u64 v[0:1], v[0:1], 0, s[16:17]
	s_mov_b32 m0, s67
	v_readfirstlane_b32 s67, v146
	global_load_lds_dwordx4 v[0:1], off
	v_lshl_add_u64 v[0:1], v[2:3], 0, s[12:13]
	s_mov_b32 m0, s67
	v_readfirstlane_b32 s67, v147
	global_load_lds_dwordx4 v[0:1], off
	v_lshl_add_u64 v[0:1], v[2:3], 0, s[16:17]
	s_mov_b32 m0, s67
	v_readfirstlane_b32 s67, v148
	global_load_lds_dwordx4 v[0:1], off
	v_lshl_add_u64 v[0:1], v[4:5], 0, s[12:13]
	s_mov_b32 m0, s67
	v_readfirstlane_b32 s67, v149
	global_load_lds_dwordx4 v[0:1], off
	v_lshl_add_u64 v[0:1], v[4:5], 0, s[16:17]
	s_mov_b32 m0, s67
	s_add_u32 s70, s6, s70
	global_load_lds_dwordx4 v[0:1], off
	s_waitcnt vmcnt(6)
	v_mov_b32_e32 v0, 0
	s_addc_u32 s71, s7, s71
	s_mov_b32 s67, -2
	v_mov_b32_e32 v1, v0
	v_mov_b32_e32 v2, v0
	v_mov_b32_e32 v3, v0
	v_mov_b32_e32 v4, v0
	v_mov_b32_e32 v5, v0
	v_mov_b32_e32 v6, v0
	v_mov_b32_e32 v7, v0
	v_mov_b32_e32 v8, v0
	v_mov_b32_e32 v9, v0
	v_mov_b32_e32 v10, v0
	v_mov_b32_e32 v11, v0
	v_mov_b32_e32 v12, v0
	v_mov_b32_e32 v13, v0
	v_mov_b32_e32 v14, v0
	v_mov_b32_e32 v15, v0
	v_mov_b32_e32 v16, v0
	v_mov_b32_e32 v17, v0
	v_mov_b32_e32 v18, v0
	v_mov_b32_e32 v19, v0
	v_mov_b32_e32 v20, v0
	v_mov_b32_e32 v21, v0
	v_mov_b32_e32 v22, v0
	v_mov_b32_e32 v23, v0
	v_mov_b32_e32 v24, v0
	v_mov_b32_e32 v25, v0
	v_mov_b32_e32 v26, v0
	v_mov_b32_e32 v27, v0
	v_mov_b32_e32 v28, v0
	v_mov_b32_e32 v29, v0
	v_mov_b32_e32 v30, v0
	v_mov_b32_e32 v31, v0
	v_mov_b32_e32 v32, v0
	v_mov_b32_e32 v33, v0
	v_mov_b32_e32 v34, v0
	v_mov_b32_e32 v35, v0
	v_mov_b32_e32 v36, v0
	v_mov_b32_e32 v37, v0
	v_mov_b32_e32 v38, v0
	v_mov_b32_e32 v39, v0
	v_mov_b32_e32 v40, v0
	v_mov_b32_e32 v41, v0
	v_mov_b32_e32 v42, v0
	v_mov_b32_e32 v43, v0
	v_mov_b32_e32 v44, v0
	v_mov_b32_e32 v45, v0
	v_mov_b32_e32 v46, v0
	v_mov_b32_e32 v47, v0
	v_mov_b32_e32 v48, v0
	v_mov_b32_e32 v49, v0
	v_mov_b32_e32 v50, v0
	v_mov_b32_e32 v51, v0
	v_mov_b32_e32 v52, v0
	v_mov_b32_e32 v53, v0
	v_mov_b32_e32 v54, v0
	v_mov_b32_e32 v55, v0
	v_mov_b32_e32 v56, v0
	v_mov_b32_e32 v57, v0
	v_mov_b32_e32 v58, v0
	v_mov_b32_e32 v59, v0
	v_mov_b32_e32 v60, v0
	v_mov_b32_e32 v61, v0
	v_mov_b32_e32 v62, v0
	v_mov_b32_e32 v63, v0
	v_mov_b32_e32 v64, v0
	v_mov_b32_e32 v65, v0
	v_mov_b32_e32 v66, v0
	v_mov_b32_e32 v67, v0
	v_mov_b32_e32 v68, v0
	v_mov_b32_e32 v69, v0
	v_mov_b32_e32 v70, v0
	v_mov_b32_e32 v71, v0
	v_mov_b32_e32 v72, v0
	v_mov_b32_e32 v73, v0
	v_mov_b32_e32 v74, v0
	v_mov_b32_e32 v75, v0
	v_mov_b32_e32 v76, v0
	v_mov_b32_e32 v77, v0
	v_mov_b32_e32 v78, v0
	v_mov_b32_e32 v79, v0
	v_mov_b32_e32 v80, v0
	v_mov_b32_e32 v81, v0
	v_mov_b32_e32 v82, v0
	v_mov_b32_e32 v83, v0
	v_mov_b32_e32 v84, v0
	v_mov_b32_e32 v85, v0
	v_mov_b32_e32 v86, v0
	v_mov_b32_e32 v87, v0
	v_mov_b32_e32 v88, v0
	v_mov_b32_e32 v89, v0
	v_mov_b32_e32 v90, v0
	v_mov_b32_e32 v91, v0
	v_mov_b32_e32 v92, v0
	v_mov_b32_e32 v93, v0
	v_mov_b32_e32 v94, v0
	v_mov_b32_e32 v95, v0
	v_mov_b32_e32 v96, v0
	v_mov_b32_e32 v97, v0
	v_mov_b32_e32 v98, v0
	v_mov_b32_e32 v99, v0
	v_mov_b32_e32 v100, v0
	v_mov_b32_e32 v101, v0
	v_mov_b32_e32 v102, v0
	v_mov_b32_e32 v103, v0
	v_mov_b32_e32 v104, v0
	v_mov_b32_e32 v105, v0
	v_mov_b32_e32 v106, v0
	v_mov_b32_e32 v107, v0
	v_mov_b32_e32 v108, v0
	v_mov_b32_e32 v109, v0
	v_mov_b32_e32 v110, v0
	v_mov_b32_e32 v111, v0
	v_mov_b32_e32 v112, v0
	v_mov_b32_e32 v113, v0
	v_mov_b32_e32 v114, v0
	v_mov_b32_e32 v115, v0
	v_mov_b32_e32 v116, v0
	v_mov_b32_e32 v117, v0
	v_mov_b32_e32 v118, v0
	v_mov_b32_e32 v119, v0
	v_mov_b32_e32 v120, v0
	v_mov_b32_e32 v121, v0
	v_mov_b32_e32 v122, v0
	v_mov_b32_e32 v123, v0
	v_mov_b32_e32 v124, v0
	v_mov_b32_e32 v125, v0
	v_mov_b32_e32 v126, v0
	v_mov_b32_e32 v127, v0
	s_barrier
; #define STAGE(P, BASE, br, kt) do { const char* _gb = (const char*)(BASE) + ((size_t)(br) * K + (size_t)(kt) * BK) * 2; \
;     __builtin_amdgcn_global_load_lds((const unsigned*)(_gb + loff0), (unsigned*)((char*)(P) + tid * 16), 16, 0, 0); \
;     __builtin_amdgcn_global_load_lds((const unsigned*)(_gb + (size_t)K * 128 + loff0), (unsigned*)((char*)(P) + tid * 16 + 8192), 16, 0, 0); } while (0)
; #define LDA(dst, b, h) for (int m = 0; m < 4; ++m) { \
;     dst[m][0] = *reinterpret_cast<const bf16x8*>((char*)SA(b, h) + aoff0 + m * 2048); \
;     dst[m][1] = *reinterpret_cast<const bf16x8*>((char*)SA(b, h) + aoff1 + m * 2048); }
; #define LDB(dst, b, h) for (int n = 0; n < 2; ++n) { \
;     dst[n][0] = *reinterpret_cast<const bf16x8*>((char*)SB(b, h) + boff0 + n * 256); \
;     dst[n][1] = *reinterpret_cast<const bf16x8*>((char*)SB(b, h) + boff1 + n * 256); }
; #define MMA(ai, bj, At, Btf) do { __builtin_amdgcn_s_setprio(1); \
;     for (int m = 0; m < 4; ++m) for (int n = 0; n < 2; ++n) for (int k = 0; k < 2; ++k) \
;       acc[ai][bj][m][n] = __builtin_amdgcn_mfma_f32_16x16x32_bf16(Btf[n][k], At[m][k], acc[ai][bj][m][n], 0, 0, 0); \
;     __builtin_amdgcn_s_setprio(0); } while (0)
; #define WAIT_V(n) asm volatile("s_waitcnt vmcnt(" #n ")" ::: "memory")
; #define WAIT_L(n) asm volatile("s_waitcnt lgkmcnt(" #n ")" ::: "memory")
; #define BAR __builtin_amdgcn_s_barrier()
; #define SCHED __builtin_amdgcn_sched_barrier(0)
; template <int EPI> ...
;     ...
;     LDB(B0, 0, 0); SCHED; LDA(At, 0, 0); STAGE(SA(1, 1), A, brow + HALF, t + 1);
;     WAIT_L(8); BAR; WAIT_L(0); MMA(0, 0, At, B0); BAR; SCHED;
;     LDB(B1, 0, 1); STAGE(SB(0, 0), Bt, bcol, t + 2);
;     BAR; WAIT_L(0); MMA(0, 1, At, B1); BAR;
;     LDA(At, 0, 1); STAGE(SA(0, 0), A, brow, t + 2);
;     BAR; WAIT_L(0); MMA(1, 0, At, B0); BAR; SCHED;
;     STAGE(SB(0, 1), Bt, bcol + HALF, t + 2);
;     WAIT_V(6); BAR; MMA(1, 1, At, B1); BAR;
.LBB0_277:
	ds_read_b128 v[162:165], v153
	ds_read_b128 v[166:169], v153 offset:256
	ds_read_b128 v[170:173], v154
	ds_read_b128 v[174:177], v154 offset:256
	v_lshl_add_u64 v[226:227], s[70:71], 0, v[130:131]
	v_readfirstlane_b32 s72, v151
	v_lshl_add_u64 v[210:211], v[226:227], 0, s[18:19]
	s_mov_b32 m0, s72
	v_readfirstlane_b32 s72, v152
	ds_read_b128 v[178:181], v150
	ds_read_b128 v[182:185], v150 offset:1024
	ds_read_b128 v[186:189], v150 offset:2048
	ds_read_b128 v[190:193], v150 offset:3072
	ds_read_b128 v[194:197], v150 offset:4096
	ds_read_b128 v[198:201], v150 offset:5120
	ds_read_b128 v[202:205], v150 offset:6144
	ds_read_b128 v[206:209], v150 offset:7168
	global_load_lds_dwordx4 v[210:211], off
	v_lshl_add_u64 v[210:211], v[226:227], 0, s[20:21]
	s_mov_b32 m0, s72
	s_nop 0
	global_load_lds_dwordx4 v[210:211], off
	s_waitcnt lgkmcnt(8)
	s_barrier
	s_waitcnt lgkmcnt(0)
	s_setprio 1
	s_waitcnt lgkmcnt(0)
	v_mfma_f32_16x16x32_bf16 v[124:127], v[162:165], v[178:181], v[124:127]
	v_mfma_f32_16x16x32_bf16 v[120:123], v[166:169], v[178:181], v[120:123]
	v_mfma_f32_16x16x32_bf16 v[116:119], v[162:165], v[186:189], v[116:119]
	v_mfma_f32_16x16x32_bf16 v[112:115], v[166:169], v[186:189], v[112:115]
	v_mfma_f32_16x16x32_bf16 v[108:111], v[162:165], v[194:197], v[108:111]
	v_mfma_f32_16x16x32_bf16 v[104:107], v[166:169], v[194:197], v[104:107]
	v_mfma_f32_16x16x32_bf16 v[100:103], v[162:165], v[202:205], v[100:103]
	v_mfma_f32_16x16x32_bf16 v[96:99], v[166:169], v[202:205], v[96:99]
	v_mfma_f32_16x16x32_bf16 v[124:127], v[170:173], v[182:185], v[124:127]
	v_mfma_f32_16x16x32_bf16 v[120:123], v[174:177], v[182:185], v[120:123]
	v_mfma_f32_16x16x32_bf16 v[116:119], v[170:173], v[190:193], v[116:119]
	v_mfma_f32_16x16x32_bf16 v[112:115], v[174:177], v[190:193], v[112:115]
	v_mfma_f32_16x16x32_bf16 v[108:111], v[170:173], v[198:201], v[108:111]
	v_mfma_f32_16x16x32_bf16 v[104:107], v[174:177], v[198:201], v[104:107]
	v_mfma_f32_16x16x32_bf16 v[100:103], v[170:173], v[206:209], v[100:103]
	v_mfma_f32_16x16x32_bf16 v[96:99], v[174:177], v[206:209], v[96:99]
	s_setprio 0
	s_barrier
	v_lshl_add_u64 v[228:229], s[68:69], 0, v[130:131]
	v_readfirstlane_b32 s72, v136
	v_lshl_add_u64 v[230:231], v[228:229], 0, s[22:23]
	s_mov_b32 m0, s72
	v_readfirstlane_b32 s72, v137
	ds_read_b128 v[210:213], v155
	ds_read_b128 v[214:217], v155 offset:256
	ds_read_b128 v[218:221], v156
	ds_read_b128 v[222:225], v156 offset:256
	global_load_lds_dwordx4 v[230:231], off
	v_lshl_add_u64 v[230:231], v[228:229], 0, s[26:27]
	s_mov_b32 m0, s72
	s_nop 0
	global_load_lds_dwordx4 v[230:231], off
	s_barrier
	s_waitcnt lgkmcnt(0)
	s_setprio 1
	s_waitcnt lgkmcnt(0)
	v_mfma_f32_16x16x32_bf16 v[92:95], v[210:213], v[178:181], v[92:95]
	v_mfma_f32_16x16x32_bf16 v[88:91], v[214:217], v[178:181], v[88:91]
	v_mfma_f32_16x16x32_bf16 v[84:87], v[210:213], v[186:189], v[84:87]
	v_mfma_f32_16x16x32_bf16 v[80:83], v[214:217], v[186:189], v[80:83]
	v_mfma_f32_16x16x32_bf16 v[76:79], v[210:213], v[194:197], v[76:79]
	v_mfma_f32_16x16x32_bf16 v[72:75], v[214:217], v[194:197], v[72:75]
	v_mfma_f32_16x16x32_bf16 v[68:71], v[210:213], v[202:205], v[68:71]
	v_mfma_f32_16x16x32_bf16 v[64:67], v[214:217], v[202:205], v[64:67]
	v_mfma_f32_16x16x32_bf16 v[92:95], v[218:221], v[182:185], v[92:95]
	v_mfma_f32_16x16x32_bf16 v[88:91], v[222:225], v[182:185], v[88:91]
	v_mfma_f32_16x16x32_bf16 v[84:87], v[218:221], v[190:193], v[84:87]
	v_mfma_f32_16x16x32_bf16 v[80:83], v[222:225], v[190:193], v[80:83]
	v_mfma_f32_16x16x32_bf16 v[76:79], v[218:221], v[198:201], v[76:79]
	v_mfma_f32_16x16x32_bf16 v[72:75], v[222:225], v[198:201], v[72:75]
	v_mfma_f32_16x16x32_bf16 v[68:71], v[218:221], v[206:209], v[68:71]
	v_mfma_f32_16x16x32_bf16 v[64:67], v[222:225], v[206:209], v[64:67]
	s_setprio 0
	v_readfirstlane_b32 s72, v138
	v_lshl_add_u64 v[230:231], v[226:227], 0, s[28:29]
	s_mov_b32 m0, s72
	v_readfirstlane_b32 s72, v139
	s_barrier
	ds_read_b128 v[178:181], v150 offset:16384
	ds_read_b128 v[182:185], v150 offset:17408
	ds_read_b128 v[186:189], v150 offset:18432
	ds_read_b128 v[190:193], v150 offset:19456
	ds_read_b128 v[194:197], v150 offset:20480
	ds_read_b128 v[198:201], v150 offset:21504
	ds_read_b128 v[202:205], v150 offset:22528
	ds_read_b128 v[206:209], v150 offset:23552
	global_load_lds_dwordx4 v[230:231], off
	v_lshl_add_u64 v[230:231], v[226:227], 0, s[30:31]
	s_mov_b32 m0, s72
	s_nop 0
	global_load_lds_dwordx4 v[230:231], off
	s_barrier
	s_waitcnt lgkmcnt(0)
	s_setprio 1
	s_waitcnt lgkmcnt(0)
	v_mfma_f32_16x16x32_bf16 v[60:63], v[162:165], v[178:181], v[60:63]
	v_mfma_f32_16x16x32_bf16 v[56:59], v[166:169], v[178:181], v[56:59]
	v_mfma_f32_16x16x32_bf16 v[52:55], v[162:165], v[186:189], v[52:55]
	v_mfma_f32_16x16x32_bf16 v[48:51], v[166:169], v[186:189], v[48:51]
	v_mfma_f32_16x16x32_bf16 v[44:47], v[162:165], v[194:197], v[44:47]
	v_mfma_f32_16x16x32_bf16 v[40:43], v[166:169], v[194:197], v[40:43]
	v_mfma_f32_16x16x32_bf16 v[36:39], v[162:165], v[202:205], v[36:39]
	v_mfma_f32_16x16x32_bf16 v[32:35], v[166:169], v[202:205], v[32:35]
	v_mfma_f32_16x16x32_bf16 v[60:63], v[170:173], v[182:185], v[60:63]
	v_mfma_f32_16x16x32_bf16 v[56:59], v[174:177], v[182:185], v[56:59]
	v_mfma_f32_16x16x32_bf16 v[52:55], v[170:173], v[190:193], v[52:55]
	v_mfma_f32_16x16x32_bf16 v[48:51], v[174:177], v[190:193], v[48:51]
	v_mfma_f32_16x16x32_bf16 v[44:47], v[170:173], v[198:201], v[44:47]
	v_mfma_f32_16x16x32_bf16 v[40:43], v[174:177], v[198:201], v[40:43]
	v_mfma_f32_16x16x32_bf16 v[36:39], v[170:173], v[206:209], v[36:39]
	v_mfma_f32_16x16x32_bf16 v[32:35], v[174:177], v[206:209], v[32:35]
	s_setprio 0
	s_barrier
; #define STAGE(P, BASE, br, kt) do { const char* _gb = (const char*)(BASE) + ((size_t)(br) * K + (size_t)(kt) * BK) * 2; \
;     __builtin_amdgcn_global_load_lds((const unsigned*)(_gb + loff0), (unsigned*)((char*)(P) + tid * 16), 16, 0, 0); \
;     __builtin_amdgcn_global_load_lds((const unsigned*)(_gb + (size_t)K * 128 + loff0), (unsigned*)((char*)(P) + tid * 16 + 8192), 16, 0, 0); } while (0)
; #define LDA(dst, b, h) for (int m = 0; m < 4; ++m) { \
;     dst[m][0] = *reinterpret_cast<const bf16x8*>((char*)SA(b, h) + aoff0 + m * 2048); \
;     dst[m][1] = *reinterpret_cast<const bf16x8*>((char*)SA(b, h) + aoff1 + m * 2048); }
; #define LDB(dst, b, h) for (int n = 0; n < 2; ++n) { \
;     dst[n][0] = *reinterpret_cast<const bf16x8*>((char*)SB(b, h) + boff0 + n * 256); \
;     dst[n][1] = *reinterpret_cast<const bf16x8*>((char*)SB(b, h) + boff1 + n * 256); }
; #define MMA(ai, bj, At, Btf) do { __builtin_amdgcn_s_setprio(1); \
;     for (int m = 0; m < 4; ++m) for (int n = 0; n < 2; ++n) for (int k = 0; k < 2; ++k) \
;       acc[ai][bj][m][n] = __builtin_amdgcn_mfma_f32_16x16x32_bf16(Btf[n][k], At[m][k], acc[ai][bj][m][n], 0, 0, 0); \
;     __builtin_amdgcn_s_setprio(0); } while (0)
; #define WAIT_V(n) asm volatile("s_waitcnt vmcnt(" #n ")" ::: "memory")
; #define WAIT_L(n) asm volatile("s_waitcnt lgkmcnt(" #n ")" ::: "memory")
; #define BAR __builtin_amdgcn_s_barrier()
; #define SCHED __builtin_amdgcn_sched_barrier(0)
; template <int EPI> ...
;     ...
;     STAGE(SB(0, 1), Bt, bcol + HALF, t + 2);
;     WAIT_V(6); BAR; MMA(1, 1, At, B1); BAR;
;     LDB(B0, 1, 0); SCHED; LDA(At, 1, 0); STAGE(SA(0, 1), A, brow + HALF, t + 2);
;     WAIT_L(8); BAR; WAIT_L(0); MMA(0, 0, At, B0); BAR; SCHED;
;     LDB(B1, 1, 1); STAGE(SB(1, 0), Bt, bcol, t + 3);
;     BAR; WAIT_L(0); MMA(0, 1, At, B1); BAR;
;     LDA(At, 1, 1); STAGE(SA(1, 0), A, brow, t + 3);
	v_readfirstlane_b32 s72, v140
	v_lshl_add_u64 v[162:163], v[228:229], 0, s[36:37]
	s_mov_b32 m0, s72
	v_readfirstlane_b32 s72, v141
	global_load_lds_dwordx4 v[162:163], off
	v_lshl_add_u64 v[162:163], v[228:229], 0, s[38:39]
	s_mov_b32 m0, s72
	s_nop 0
	global_load_lds_dwordx4 v[162:163], off
	s_waitcnt vmcnt(6)
	s_barrier
	s_setprio 1
	v_mfma_f32_16x16x32_bf16 v[28:31], v[210:213], v[178:181], v[28:31]
	v_mfma_f32_16x16x32_bf16 v[24:27], v[214:217], v[178:181], v[24:27]
	v_mfma_f32_16x16x32_bf16 v[20:23], v[210:213], v[186:189], v[20:23]
	v_mfma_f32_16x16x32_bf16 v[16:19], v[214:217], v[186:189], v[16:19]
	v_mfma_f32_16x16x32_bf16 v[12:15], v[210:213], v[194:197], v[12:15]
	v_mfma_f32_16x16x32_bf16 v[8:11], v[214:217], v[194:197], v[8:11]
	v_mfma_f32_16x16x32_bf16 v[4:7], v[210:213], v[202:205], v[4:7]
	v_mfma_f32_16x16x32_bf16 v[0:3], v[214:217], v[202:205], v[0:3]
	v_mfma_f32_16x16x32_bf16 v[28:31], v[218:221], v[182:185], v[28:31]
	v_mfma_f32_16x16x32_bf16 v[24:27], v[222:225], v[182:185], v[24:27]
	v_mfma_f32_16x16x32_bf16 v[20:23], v[218:221], v[190:193], v[20:23]
	v_mfma_f32_16x16x32_bf16 v[16:19], v[222:225], v[190:193], v[16:19]
	v_mfma_f32_16x16x32_bf16 v[12:15], v[218:221], v[198:201], v[12:15]
	v_mfma_f32_16x16x32_bf16 v[8:11], v[222:225], v[198:201], v[8:11]
	v_mfma_f32_16x16x32_bf16 v[4:7], v[218:221], v[206:209], v[4:7]
	v_mfma_f32_16x16x32_bf16 v[0:3], v[222:225], v[206:209], v[0:3]
	s_setprio 0
	s_barrier
	ds_read_b128 v[162:165], v157
	ds_read_b128 v[166:169], v157 offset:256
	ds_read_b128 v[170:173], v158
	ds_read_b128 v[174:177], v158 offset:256
	v_readfirstlane_b32 s72, v142
	v_lshl_add_u64 v[210:211], v[226:227], 0, s[46:47]
	s_mov_b32 m0, s72
	v_readfirstlane_b32 s72, v143
	ds_read_b128 v[178:181], v150 offset:32768
	ds_read_b128 v[182:185], v150 offset:33792
	ds_read_b128 v[186:189], v150 offset:34816
	ds_read_b128 v[190:193], v150 offset:35840
	ds_read_b128 v[194:197], v150 offset:36864
	ds_read_b128 v[198:201], v150 offset:37888
	ds_read_b128 v[202:205], v150 offset:38912
	ds_read_b128 v[206:209], v150 offset:39936
	global_load_lds_dwordx4 v[210:211], off
	v_lshl_add_u64 v[210:211], v[226:227], 0, s[48:49]
	s_mov_b32 m0, s72
	s_nop 0
	global_load_lds_dwordx4 v[210:211], off
	s_waitcnt lgkmcnt(8)
	s_barrier
	s_waitcnt lgkmcnt(0)
	s_setprio 1
	s_waitcnt lgkmcnt(0)
	v_mfma_f32_16x16x32_bf16 v[124:127], v[162:165], v[178:181], v[124:127]
	v_mfma_f32_16x16x32_bf16 v[120:123], v[166:169], v[178:181], v[120:123]
	v_mfma_f32_16x16x32_bf16 v[116:119], v[162:165], v[186:189], v[116:119]
	v_mfma_f32_16x16x32_bf16 v[112:115], v[166:169], v[186:189], v[112:115]
	v_mfma_f32_16x16x32_bf16 v[108:111], v[162:165], v[194:197], v[108:111]
	v_mfma_f32_16x16x32_bf16 v[104:107], v[166:169], v[194:197], v[104:107]
	v_mfma_f32_16x16x32_bf16 v[100:103], v[162:165], v[202:205], v[100:103]
	v_mfma_f32_16x16x32_bf16 v[96:99], v[166:169], v[202:205], v[96:99]
	v_mfma_f32_16x16x32_bf16 v[124:127], v[170:173], v[182:185], v[124:127]
	v_mfma_f32_16x16x32_bf16 v[120:123], v[174:177], v[182:185], v[120:123]
	v_mfma_f32_16x16x32_bf16 v[116:119], v[170:173], v[190:193], v[116:119]
	v_mfma_f32_16x16x32_bf16 v[112:115], v[174:177], v[190:193], v[112:115]
	v_mfma_f32_16x16x32_bf16 v[108:111], v[170:173], v[198:201], v[108:111]
	v_mfma_f32_16x16x32_bf16 v[104:107], v[174:177], v[198:201], v[104:107]
	v_mfma_f32_16x16x32_bf16 v[100:103], v[170:173], v[206:209], v[100:103]
	v_mfma_f32_16x16x32_bf16 v[96:99], v[174:177], v[206:209], v[96:99]
	s_setprio 0
	s_barrier
	v_readfirstlane_b32 s72, v144
	v_lshl_add_u64 v[230:231], v[228:229], 0, s[50:51]
	s_mov_b32 m0, s72
	v_readfirstlane_b32 s72, v145
	ds_read_b128 v[210:213], v159
	ds_read_b128 v[214:217], v159 offset:256
	ds_read_b128 v[218:221], v160
	ds_read_b128 v[222:225], v160 offset:256
	global_load_lds_dwordx4 v[230:231], off
	v_lshl_add_u64 v[230:231], v[228:229], 0, s[52:53]
	s_mov_b32 m0, s72
	s_nop 0
	global_load_lds_dwordx4 v[230:231], off
	s_barrier
	s_waitcnt lgkmcnt(0)
	s_setprio 1
	s_waitcnt lgkmcnt(0)
	v_mfma_f32_16x16x32_bf16 v[92:95], v[210:213], v[178:181], v[92:95]
	v_mfma_f32_16x16x32_bf16 v[88:91], v[214:217], v[178:181], v[88:91]
	v_mfma_f32_16x16x32_bf16 v[84:87], v[210:213], v[186:189], v[84:87]
	v_mfma_f32_16x16x32_bf16 v[80:83], v[214:217], v[186:189], v[80:83]
	v_mfma_f32_16x16x32_bf16 v[76:79], v[210:213], v[194:197], v[76:79]
	v_mfma_f32_16x16x32_bf16 v[72:75], v[214:217], v[194:197], v[72:75]
	v_mfma_f32_16x16x32_bf16 v[68:71], v[210:213], v[202:205], v[68:71]
	v_mfma_f32_16x16x32_bf16 v[64:67], v[214:217], v[202:205], v[64:67]
	v_mfma_f32_16x16x32_bf16 v[92:95], v[218:221], v[182:185], v[92:95]
	v_mfma_f32_16x16x32_bf16 v[88:91], v[222:225], v[182:185], v[88:91]
	v_mfma_f32_16x16x32_bf16 v[84:87], v[218:221], v[190:193], v[84:87]
	v_mfma_f32_16x16x32_bf16 v[80:83], v[222:225], v[190:193], v[80:83]
	v_mfma_f32_16x16x32_bf16 v[76:79], v[218:221], v[198:201], v[76:79]
	v_mfma_f32_16x16x32_bf16 v[72:75], v[222:225], v[198:201], v[72:75]
	v_mfma_f32_16x16x32_bf16 v[68:71], v[218:221], v[206:209], v[68:71]
	v_mfma_f32_16x16x32_bf16 v[64:67], v[222:225], v[206:209], v[64:67]
	s_setprio 0
	v_readfirstlane_b32 s72, v146
	v_lshl_add_u64 v[230:231], v[226:227], 0, s[54:55]
	s_mov_b32 m0, s72
	v_readfirstlane_b32 s72, v147
	s_barrier
	ds_read_b128 v[178:181], v150 offset:49152
	ds_read_b128 v[182:185], v150 offset:50176
	ds_read_b128 v[186:189], v150 offset:51200
	ds_read_b128 v[190:193], v150 offset:52224
	ds_read_b128 v[194:197], v150 offset:53248
	ds_read_b128 v[198:201], v150 offset:54272
	ds_read_b128 v[202:205], v150 offset:55296
	ds_read_b128 v[206:209], v150 offset:56320
	global_load_lds_dwordx4 v[230:231], off
	v_lshl_add_u64 v[226:227], v[226:227], 0, s[56:57]
	s_mov_b32 m0, s72
	s_nop 0
	global_load_lds_dwordx4 v[226:227], off
	s_barrier
; #define STAGE(P, BASE, br, kt) do { const char* _gb = (const char*)(BASE) + ((size_t)(br) * K + (size_t)(kt) * BK) * 2; \
;     __builtin_amdgcn_global_load_lds((const unsigned*)(_gb + loff0), (unsigned*)((char*)(P) + tid * 16), 16, 0, 0); \
;     __builtin_amdgcn_global_load_lds((const unsigned*)(_gb + (size_t)K * 128 + loff0), (unsigned*)((char*)(P) + tid * 16 + 8192), 16, 0, 0); } while (0)
; #define LDA(dst, b, h) for (int m = 0; m < 4; ++m) { \
;     dst[m][0] = *reinterpret_cast<const bf16x8*>((char*)SA(b, h) + aoff0 + m * 2048); \
;     dst[m][1] = *reinterpret_cast<const bf16x8*>((char*)SA(b, h) + aoff1 + m * 2048); }
; #define LDB(dst, b, h) for (int n = 0; n < 2; ++n) { \
;     dst[n][0] = *reinterpret_cast<const bf16x8*>((char*)SB(b, h) + boff0 + n * 256); \
;     dst[n][1] = *reinterpret_cast<const bf16x8*>((char*)SB(b, h) + boff1 + n * 256); }
; #define MMA(ai, bj, At, Btf) do { __builtin_amdgcn_s_setprio(1); \
;     for (int m = 0; m < 4; ++m) for (int n = 0; n < 2; ++n) for (int k = 0; k < 2; ++k) \
;       acc[ai][bj][m][n] = __builtin_amdgcn_mfma_f32_16x16x32_bf16(Btf[n][k], At[m][k], acc[ai][bj][m][n], 0, 0, 0); \
;     __builtin_amdgcn_s_setprio(0); } while (0)
; #define WAIT_V(n) asm volatile("s_waitcnt vmcnt(" #n ")" ::: "memory")
; #define WAIT_L(n) asm volatile("s_waitcnt lgkmcnt(" #n ")" ::: "memory")
; #define BAR __builtin_amdgcn_s_barrier()
; #define SCHED __builtin_amdgcn_sched_barrier(0)
; template <int EPI> ...
;     ...
;     BAR; WAIT_L(0); MMA(1, 0, At, B0); BAR; SCHED;
;     STAGE(SB(1, 1), Bt, bcol + HALF, t + 3);
;     WAIT_V(6); BAR; MMA(1, 1, At, B1); BAR;
;   }
;   { LDB(B0, 0, 0); LDA(At, 0, 0); STAGE(SA(1, 1), A, brow + HALF, nt - 1);
;     BAR; WAIT_L(0); MMA(0, 0, At, B0); BAR;
;     LDB(B1, 0, 1); BAR; WAIT_L(0); MMA(0, 1, At, B1); BAR;
	s_waitcnt lgkmcnt(0)
	s_setprio 1
	s_waitcnt lgkmcnt(0)
	v_mfma_f32_16x16x32_bf16 v[60:63], v[162:165], v[178:181], v[60:63]
	v_mfma_f32_16x16x32_bf16 v[56:59], v[166:169], v[178:181], v[56:59]
	v_mfma_f32_16x16x32_bf16 v[52:55], v[162:165], v[186:189], v[52:55]
	v_mfma_f32_16x16x32_bf16 v[48:51], v[166:169], v[186:189], v[48:51]
	v_mfma_f32_16x16x32_bf16 v[44:47], v[162:165], v[194:197], v[44:47]
	v_mfma_f32_16x16x32_bf16 v[40:43], v[166:169], v[194:197], v[40:43]
	v_mfma_f32_16x16x32_bf16 v[36:39], v[162:165], v[202:205], v[36:39]
	v_mfma_f32_16x16x32_bf16 v[32:35], v[166:169], v[202:205], v[32:35]
	v_mfma_f32_16x16x32_bf16 v[60:63], v[170:173], v[182:185], v[60:63]
	v_mfma_f32_16x16x32_bf16 v[56:59], v[174:177], v[182:185], v[56:59]
	v_mfma_f32_16x16x32_bf16 v[52:55], v[170:173], v[190:193], v[52:55]
	v_mfma_f32_16x16x32_bf16 v[48:51], v[174:177], v[190:193], v[48:51]
	v_mfma_f32_16x16x32_bf16 v[44:47], v[170:173], v[198:201], v[44:47]
	v_mfma_f32_16x16x32_bf16 v[40:43], v[174:177], v[198:201], v[40:43]
	v_mfma_f32_16x16x32_bf16 v[36:39], v[170:173], v[206:209], v[36:39]
	v_mfma_f32_16x16x32_bf16 v[32:35], v[174:177], v[206:209], v[32:35]
	s_setprio 0
	s_barrier
	v_readfirstlane_b32 s72, v148
	v_lshl_add_u64 v[162:163], v[228:229], 0, s[58:59]
	s_mov_b32 m0, s72
	v_readfirstlane_b32 s72, v149
	global_load_lds_dwordx4 v[162:163], off
	v_lshl_add_u64 v[162:163], v[228:229], 0, s[60:61]
	s_mov_b32 m0, s72
	s_nop 0
	global_load_lds_dwordx4 v[162:163], off
	s_waitcnt vmcnt(6)
	s_barrier
	s_setprio 1
	v_mfma_f32_16x16x32_bf16 v[28:31], v[210:213], v[178:181], v[28:31]
	v_mfma_f32_16x16x32_bf16 v[24:27], v[214:217], v[178:181], v[24:27]
	v_mfma_f32_16x16x32_bf16 v[20:23], v[210:213], v[186:189], v[20:23]
	v_mfma_f32_16x16x32_bf16 v[16:19], v[214:217], v[186:189], v[16:19]
	v_mfma_f32_16x16x32_bf16 v[12:15], v[210:213], v[194:197], v[12:15]
	v_mfma_f32_16x16x32_bf16 v[8:11], v[214:217], v[194:197], v[8:11]
	v_mfma_f32_16x16x32_bf16 v[4:7], v[210:213], v[202:205], v[4:7]
	v_mfma_f32_16x16x32_bf16 v[0:3], v[214:217], v[202:205], v[0:3]
	v_mfma_f32_16x16x32_bf16 v[28:31], v[218:221], v[182:185], v[28:31]
	v_mfma_f32_16x16x32_bf16 v[24:27], v[222:225], v[182:185], v[24:27]
	v_mfma_f32_16x16x32_bf16 v[20:23], v[218:221], v[190:193], v[20:23]
	v_mfma_f32_16x16x32_bf16 v[16:19], v[222:225], v[190:193], v[16:19]
	v_mfma_f32_16x16x32_bf16 v[12:15], v[218:221], v[198:201], v[12:15]
	v_mfma_f32_16x16x32_bf16 v[8:11], v[222:225], v[198:201], v[8:11]
	v_mfma_f32_16x16x32_bf16 v[4:7], v[218:221], v[206:209], v[4:7]
	v_mfma_f32_16x16x32_bf16 v[0:3], v[222:225], v[206:209], v[0:3]
	s_setprio 0
	s_add_i32 s67, s67, 2
	s_add_u32 s70, s70, 0x100
	s_addc_u32 s71, s71, 0
	s_add_u32 s68, s68, 0x100
	s_addc_u32 s69, s69, 0
	s_cmp_lt_u32 s67, 28
	s_barrier
	s_cbranch_scc1 .LBB0_277
	v_readfirstlane_b32 s67, v151
	v_lshl_add_u64 v[210:211], v[132:133], 0, s[62:63]
	s_mov_b32 m0, s67
	v_readfirstlane_b32 s67, v152
	ds_read_b128 v[162:165], v153
	ds_read_b128 v[166:169], v153 offset:256
	ds_read_b128 v[170:173], v154
	ds_read_b128 v[174:177], v154 offset:256
	ds_read_b128 v[178:181], v150
	ds_read_b128 v[182:185], v150 offset:1024
	ds_read_b128 v[186:189], v150 offset:2048
	ds_read_b128 v[190:193], v150 offset:3072
	ds_read_b128 v[194:197], v150 offset:4096
	ds_read_b128 v[198:201], v150 offset:5120
	ds_read_b128 v[202:205], v150 offset:6144
	ds_read_b128 v[206:209], v150 offset:7168
	global_load_lds_dwordx4 v[210:211], off
	v_lshl_add_u64 v[132:133], v[132:133], 0, s[64:65]
	s_mov_b32 m0, s67
	s_nop 0
	global_load_lds_dwordx4 v[132:133], off
	s_barrier
	s_waitcnt lgkmcnt(0)
	s_setprio 1
	s_waitcnt lgkmcnt(0)
	v_mfma_f32_16x16x32_bf16 v[124:127], v[162:165], v[178:181], v[124:127]
	v_mfma_f32_16x16x32_bf16 v[116:119], v[162:165], v[186:189], v[116:119]
	v_mfma_f32_16x16x32_bf16 v[108:111], v[162:165], v[194:197], v[108:111]
	v_mfma_f32_16x16x32_bf16 v[100:103], v[162:165], v[202:205], v[100:103]
	v_mfma_f32_16x16x32_bf16 v[124:127], v[170:173], v[182:185], v[124:127]
	v_mfma_f32_16x16x32_bf16 v[120:123], v[166:169], v[178:181], v[120:123]
	v_mfma_f32_16x16x32_bf16 v[116:119], v[170:173], v[190:193], v[116:119]
	v_mfma_f32_16x16x32_bf16 v[112:115], v[166:169], v[186:189], v[112:115]
	v_mfma_f32_16x16x32_bf16 v[108:111], v[170:173], v[198:201], v[108:111]
	v_mfma_f32_16x16x32_bf16 v[104:107], v[166:169], v[194:197], v[104:107]
	v_mfma_f32_16x16x32_bf16 v[100:103], v[170:173], v[206:209], v[100:103]
	v_mfma_f32_16x16x32_bf16 v[96:99], v[166:169], v[202:205], v[96:99]
	v_mfma_f32_16x16x32_bf16 v[210:213], v[174:177], v[182:185], v[120:123]
	v_mfma_f32_16x16x32_bf16 v[214:217], v[174:177], v[190:193], v[112:115]
	v_mfma_f32_16x16x32_bf16 v[218:221], v[174:177], v[198:201], v[104:107]
	v_mfma_f32_16x16x32_bf16 v[222:225], v[174:177], v[206:209], v[96:99]
	s_setprio 0
	s_barrier
	s_nop 1
	ds_read_b128 v[96:99], v155
	ds_read_b128 v[104:107], v155 offset:256
	ds_read_b128 v[112:115], v156
	ds_read_b128 v[120:123], v156 offset:256
	s_barrier
	s_waitcnt lgkmcnt(0)
	s_setprio 1
	s_waitcnt lgkmcnt(0)
	v_mfma_f32_16x16x32_bf16 v[92:95], v[96:99], v[178:181], v[92:95]
	v_mfma_f32_16x16x32_bf16 v[84:87], v[96:99], v[186:189], v[84:87]
	v_mfma_f32_16x16x32_bf16 v[76:79], v[96:99], v[194:197], v[76:79]
	v_mfma_f32_16x16x32_bf16 v[68:71], v[96:99], v[202:205], v[68:71]
	v_mfma_f32_16x16x32_bf16 v[92:95], v[112:115], v[182:185], v[92:95]
	v_mfma_f32_16x16x32_bf16 v[88:91], v[104:107], v[178:181], v[88:91]
	v_mfma_f32_16x16x32_bf16 v[84:87], v[112:115], v[190:193], v[84:87]
	v_mfma_f32_16x16x32_bf16 v[80:83], v[104:107], v[186:189], v[80:83]
	v_mfma_f32_16x16x32_bf16 v[76:79], v[112:115], v[198:201], v[76:79]
	v_mfma_f32_16x16x32_bf16 v[72:75], v[104:107], v[194:197], v[72:75]
	v_mfma_f32_16x16x32_bf16 v[68:71], v[112:115], v[206:209], v[68:71]
	v_mfma_f32_16x16x32_bf16 v[64:67], v[104:107], v[202:205], v[64:67]
	v_mfma_f32_16x16x32_bf16 v[178:181], v[120:123], v[182:185], v[88:91]
	v_mfma_f32_16x16x32_bf16 v[182:185], v[120:123], v[190:193], v[80:83]
	v_mfma_f32_16x16x32_bf16 v[186:189], v[120:123], v[198:201], v[72:75]
	v_mfma_f32_16x16x32_bf16 v[190:193], v[120:123], v[206:209], v[64:67]
	s_setprio 0
	s_barrier
; #define LDA(dst, b, h) for (int m = 0; m < 4; ++m) { \
;     dst[m][0] = *reinterpret_cast<const bf16x8*>((char*)SA(b, h) + aoff0 + m * 2048); \
;     dst[m][1] = *reinterpret_cast<const bf16x8*>((char*)SA(b, h) + aoff1 + m * 2048); }
; #define LDB(dst, b, h) for (int n = 0; n < 2; ++n) { \
;     dst[n][0] = *reinterpret_cast<const bf16x8*>((char*)SB(b, h) + boff0 + n * 256); \
;     dst[n][1] = *reinterpret_cast<const bf16x8*>((char*)SB(b, h) + boff1 + n * 256); }
; #define MMA(ai, bj, At, Btf) do { __builtin_amdgcn_s_setprio(1); \
;     for (int m = 0; m < 4; ++m) for (int n = 0; n < 2; ++n) for (int k = 0; k < 2; ++k) \
;       acc[ai][bj][m][n] = __builtin_amdgcn_mfma_f32_16x16x32_bf16(Btf[n][k], At[m][k], acc[ai][bj][m][n], 0, 0, 0); \
;     __builtin_amdgcn_s_setprio(0); } while (0)
; #define WAIT_V(n) asm volatile("s_waitcnt vmcnt(" #n ")" ::: "memory")
; #define WAIT_L(n) asm volatile("s_waitcnt lgkmcnt(" #n ")" ::: "memory")
; #define BAR __builtin_amdgcn_s_barrier()
; template <int EPI> ...
;     ...
;     LDB(B1, 0, 1); BAR; WAIT_L(0); MMA(0, 1, At, B1); BAR;
;     LDA(At, 0, 1); WAIT_V(4); BAR; WAIT_L(0); MMA(1, 0, At, B0); MMA(1, 1, At, B1); BAR; }
;   { LDB(B0, 1, 0); LDA(At, 1, 0); WAIT_V(2); BAR; WAIT_L(0); MMA(0, 0, At, B0); BAR;
;     LDB(B1, 1, 1); WAIT_V(0); BAR; WAIT_L(0); MMA(0, 1, At, B1); BAR;
	s_nop 1
	ds_read_b128 v[64:67], v150 offset:16384
	ds_read_b128 v[72:75], v150 offset:17408
	ds_read_b128 v[80:83], v150 offset:18432
	ds_read_b128 v[88:91], v150 offset:19456
	ds_read_b128 v[194:197], v150 offset:20480
	ds_read_b128 v[198:201], v150 offset:21504
	ds_read_b128 v[202:205], v150 offset:22528
	ds_read_b128 v[206:209], v150 offset:23552
	s_waitcnt vmcnt(4)
	s_barrier
	s_waitcnt lgkmcnt(0)
	s_setprio 1
	s_waitcnt lgkmcnt(0)
	v_mfma_f32_16x16x32_bf16 v[60:63], v[162:165], v[64:67], v[60:63]
	v_mfma_f32_16x16x32_bf16 v[56:59], v[166:169], v[64:67], v[56:59]
	v_mfma_f32_16x16x32_bf16 v[52:55], v[162:165], v[80:83], v[52:55]
	v_mfma_f32_16x16x32_bf16 v[40:43], v[166:169], v[194:197], v[40:43]
	v_mfma_f32_16x16x32_bf16 v[36:39], v[162:165], v[202:205], v[36:39]
	v_mfma_f32_16x16x32_bf16 v[60:63], v[170:173], v[72:75], v[60:63]
	v_mfma_f32_16x16x32_bf16 v[56:59], v[174:177], v[72:75], v[56:59]
	v_mfma_f32_16x16x32_bf16 v[52:55], v[170:173], v[88:91], v[52:55]
	v_mfma_f32_16x16x32_bf16 v[48:51], v[166:169], v[80:83], v[48:51]
	v_mfma_f32_16x16x32_bf16 v[44:47], v[162:165], v[194:197], v[44:47]
	v_mfma_f32_16x16x32_bf16 v[40:43], v[174:177], v[198:201], v[40:43]
	v_mfma_f32_16x16x32_bf16 v[36:39], v[170:173], v[206:209], v[36:39]
	v_mfma_f32_16x16x32_bf16 v[32:35], v[166:169], v[202:205], v[32:35]
	v_mfma_f32_16x16x32_bf16 v[226:229], v[174:177], v[88:91], v[48:51]
	v_mfma_f32_16x16x32_bf16 v[230:233], v[170:173], v[198:201], v[44:47]
	v_mfma_f32_16x16x32_bf16 v[162:165], v[174:177], v[206:209], v[32:35]
	s_setprio 0
	s_setprio 1
	v_mfma_f32_16x16x32_bf16 v[24:27], v[104:107], v[64:67], v[24:27]
	v_mfma_f32_16x16x32_bf16 v[20:23], v[96:99], v[80:83], v[20:23]
	v_mfma_f32_16x16x32_bf16 v[8:11], v[104:107], v[194:197], v[8:11]
	v_mfma_f32_16x16x32_bf16 v[4:7], v[96:99], v[202:205], v[4:7]
	v_mfma_f32_16x16x32_bf16 v[28:31], v[96:99], v[64:67], v[28:31]
	v_mfma_f32_16x16x32_bf16 v[24:27], v[120:123], v[72:75], v[24:27]
	v_mfma_f32_16x16x32_bf16 v[20:23], v[112:115], v[88:91], v[20:23]
	v_mfma_f32_16x16x32_bf16 v[16:19], v[104:107], v[80:83], v[16:19]
	v_mfma_f32_16x16x32_bf16 v[12:15], v[96:99], v[194:197], v[12:15]
	v_mfma_f32_16x16x32_bf16 v[8:11], v[120:123], v[198:201], v[8:11]
	v_mfma_f32_16x16x32_bf16 v[4:7], v[112:115], v[206:209], v[4:7]
	v_mfma_f32_16x16x32_bf16 v[0:3], v[104:107], v[202:205], v[0:3]
	v_mfma_f32_16x16x32_bf16 v[166:169], v[112:115], v[72:75], v[28:31]
	v_mfma_f32_16x16x32_bf16 v[170:173], v[120:123], v[88:91], v[16:19]
	v_mfma_f32_16x16x32_bf16 v[174:177], v[112:115], v[198:201], v[12:15]
	v_mfma_f32_16x16x32_bf16 v[194:197], v[120:123], v[206:209], v[0:3]
	s_setprio 0
	s_barrier
	s_nop 1
	ds_read_b128 v[0:3], v157
	ds_read_b128 v[198:201], v157 offset:256
	ds_read_b128 v[12:15], v158
	ds_read_b128 v[202:205], v158 offset:256
	ds_read_b128 v[16:19], v150 offset:32768
	ds_read_b128 v[28:31], v150 offset:33792
	ds_read_b128 v[32:35], v150 offset:34816
	ds_read_b128 v[44:47], v150 offset:35840
	ds_read_b128 v[48:51], v150 offset:36864
	ds_read_b128 v[206:209], v150 offset:37888
	ds_read_b128 v[234:237], v150 offset:38912
	ds_read_b128 v[238:241], v150 offset:39936
	s_waitcnt vmcnt(2)
	s_barrier
	s_waitcnt lgkmcnt(0)
	s_setprio 1
	s_waitcnt lgkmcnt(0)
	v_mfma_f32_16x16x32_bf16 v[64:67], v[0:3], v[16:19], v[124:127]
	v_mfma_f32_16x16x32_bf16 v[120:123], v[12:15], v[28:31], v[64:67]
	v_mfma_f32_16x16x32_bf16 v[64:67], v[198:201], v[16:19], v[210:213]
	v_mfma_f32_16x16x32_bf16 v[112:115], v[202:205], v[28:31], v[64:67]
	v_mfma_f32_16x16x32_bf16 v[64:67], v[0:3], v[32:35], v[116:119]
	v_mfma_f32_16x16x32_bf16 v[104:107], v[12:15], v[44:47], v[64:67]
	v_mfma_f32_16x16x32_bf16 v[64:67], v[198:201], v[32:35], v[214:217]
	v_mfma_f32_16x16x32_bf16 v[96:99], v[202:205], v[44:47], v[64:67]
	v_mfma_f32_16x16x32_bf16 v[64:67], v[0:3], v[48:51], v[108:111]
	v_mfma_f32_16x16x32_bf16 v[88:91], v[12:15], v[206:209], v[64:67]
	v_mfma_f32_16x16x32_bf16 v[64:67], v[198:201], v[48:51], v[218:221]
	v_mfma_f32_16x16x32_bf16 v[80:83], v[202:205], v[206:209], v[64:67]
	v_mfma_f32_16x16x32_bf16 v[64:67], v[0:3], v[234:237], v[100:103]
	v_mfma_f32_16x16x32_bf16 v[72:75], v[12:15], v[238:241], v[64:67]
	v_mfma_f32_16x16x32_bf16 v[64:67], v[198:201], v[234:237], v[222:225]
	v_mfma_f32_16x16x32_bf16 v[64:67], v[202:205], v[238:241], v[64:67]
	s_setprio 0
	s_barrier
; #define LDA(dst, b, h) for (int m = 0; m < 4; ++m) { \
;     dst[m][0] = *reinterpret_cast<const bf16x8*>((char*)SA(b, h) + aoff0 + m * 2048); \
;     dst[m][1] = *reinterpret_cast<const bf16x8*>((char*)SA(b, h) + aoff1 + m * 2048); }
; #define LDB(dst, b, h) for (int n = 0; n < 2; ++n) { \
;     dst[n][0] = *reinterpret_cast<const bf16x8*>((char*)SB(b, h) + boff0 + n * 256); \
;     dst[n][1] = *reinterpret_cast<const bf16x8*>((char*)SB(b, h) + boff1 + n * 256); }
; #define MMA(ai, bj, At, Btf) do { __builtin_amdgcn_s_setprio(1); \
;     for (int m = 0; m < 4; ++m) for (int n = 0; n < 2; ++n) for (int k = 0; k < 2; ++k) \
;       acc[ai][bj][m][n] = __builtin_amdgcn_mfma_f32_16x16x32_bf16(Btf[n][k], At[m][k], acc[ai][bj][m][n], 0, 0, 0); \
;     __builtin_amdgcn_s_setprio(0); } while (0)
; #define WAIT_V(n) asm volatile("s_waitcnt vmcnt(" #n ")" ::: "memory")
; #define WAIT_L(n) asm volatile("s_waitcnt lgkmcnt(" #n ")" ::: "memory")
; #define BAR __builtin_amdgcn_s_barrier()
; template <int EPI> ...
;     ...
;     LDB(B1, 1, 1); WAIT_V(0); BAR; WAIT_L(0); MMA(0, 1, At, B1); BAR;
;     LDA(At, 1, 1); BAR; WAIT_L(0); MMA(1, 0, At, B0); MMA(1, 1, At, B1); BAR; }
;   if (wr == 0) BAR;
	ds_read_b128 v[210:213], v159
	ds_read_b128 v[214:217], v159 offset:256
	ds_read_b128 v[218:221], v160
	ds_read_b128 v[222:225], v160 offset:256
	s_waitcnt vmcnt(0)
	s_barrier
	s_waitcnt lgkmcnt(0)
	s_setprio 1
	s_waitcnt lgkmcnt(0)
	v_mfma_f32_16x16x32_bf16 v[92:95], v[210:213], v[16:19], v[92:95]
	v_mfma_f32_16x16x32_bf16 v[16:19], v[214:217], v[16:19], v[178:181]
	v_mfma_f32_16x16x32_bf16 v[116:119], v[222:225], v[28:31], v[16:19]
	v_mfma_f32_16x16x32_bf16 v[16:19], v[210:213], v[32:35], v[84:87]
	v_mfma_f32_16x16x32_bf16 v[108:111], v[218:221], v[44:47], v[16:19]
	v_mfma_f32_16x16x32_bf16 v[16:19], v[214:217], v[32:35], v[182:185]
	v_mfma_f32_16x16x32_bf16 v[100:103], v[222:225], v[44:47], v[16:19]
	v_mfma_f32_16x16x32_bf16 v[16:19], v[210:213], v[48:51], v[76:79]
	v_mfma_f32_16x16x32_bf16 v[124:127], v[218:221], v[28:31], v[92:95]
	v_mfma_f32_16x16x32_bf16 v[92:95], v[218:221], v[206:209], v[16:19]
	v_mfma_f32_16x16x32_bf16 v[16:19], v[214:217], v[48:51], v[186:189]
	v_mfma_f32_16x16x32_bf16 v[84:87], v[222:225], v[206:209], v[16:19]
	v_mfma_f32_16x16x32_bf16 v[16:19], v[210:213], v[234:237], v[68:71]
	v_mfma_f32_16x16x32_bf16 v[76:79], v[218:221], v[238:241], v[16:19]
	v_mfma_f32_16x16x32_bf16 v[16:19], v[214:217], v[234:237], v[190:193]
	v_mfma_f32_16x16x32_bf16 v[68:71], v[222:225], v[238:241], v[16:19]
	s_setprio 0
	s_barrier
	ds_read_b128 v[178:181], v150 offset:49152
	ds_read_b128 v[182:185], v150 offset:50176
	ds_read_b128 v[186:189], v150 offset:51200
	ds_read_b128 v[190:193], v150 offset:52224
	ds_read_b128 v[206:209], v150 offset:53248
	ds_read_b128 v[234:237], v150 offset:54272
	ds_read_b128 v[238:241], v150 offset:55296
	ds_read_b128 v[242:245], v150 offset:56320
	s_barrier
	s_waitcnt lgkmcnt(0)
	s_setprio 1
	s_waitcnt lgkmcnt(0)
	v_mfma_f32_16x16x32_bf16 v[16:19], v[0:3], v[178:181], v[60:63]
	v_mfma_f32_16x16x32_bf16 v[60:63], v[12:15], v[182:185], v[16:19]
	v_mfma_f32_16x16x32_bf16 v[16:19], v[198:201], v[178:181], v[56:59]
	v_mfma_f32_16x16x32_bf16 v[48:51], v[202:205], v[182:185], v[16:19]
	v_mfma_f32_16x16x32_bf16 v[16:19], v[0:3], v[186:189], v[52:55]
	v_mfma_f32_16x16x32_bf16 v[44:47], v[12:15], v[190:193], v[16:19]
	v_mfma_f32_16x16x32_bf16 v[16:19], v[198:201], v[186:189], v[226:229]
	v_mfma_f32_16x16x32_bf16 v[32:35], v[202:205], v[190:193], v[16:19]
	v_mfma_f32_16x16x32_bf16 v[16:19], v[0:3], v[206:209], v[230:233]
	v_mfma_f32_16x16x32_bf16 v[0:3], v[0:3], v[238:241], v[36:39]
	v_mfma_f32_16x16x32_bf16 v[28:31], v[12:15], v[234:237], v[16:19]
	v_mfma_f32_16x16x32_bf16 v[16:19], v[198:201], v[206:209], v[40:43]
	v_mfma_f32_16x16x32_bf16 v[12:15], v[12:15], v[242:245], v[0:3]
	v_mfma_f32_16x16x32_bf16 v[0:3], v[198:201], v[238:241], v[162:165]
	v_mfma_f32_16x16x32_bf16 v[16:19], v[202:205], v[234:237], v[16:19]
	v_mfma_f32_16x16x32_bf16 v[0:3], v[202:205], v[242:245], v[0:3]
	s_setprio 0
	s_setprio 1
	v_mfma_f32_16x16x32_bf16 v[20:23], v[210:213], v[186:189], v[20:23]
	v_mfma_f32_16x16x32_bf16 v[36:39], v[210:213], v[178:181], v[166:169]
	v_mfma_f32_16x16x32_bf16 v[40:43], v[218:221], v[190:193], v[20:23]
	v_mfma_f32_16x16x32_bf16 v[20:23], v[214:217], v[186:189], v[170:173]
	v_mfma_f32_16x16x32_bf16 v[56:59], v[218:221], v[182:185], v[36:39]
	v_mfma_f32_16x16x32_bf16 v[24:27], v[214:217], v[178:181], v[24:27]
	v_mfma_f32_16x16x32_bf16 v[36:39], v[222:225], v[190:193], v[20:23]
	v_mfma_f32_16x16x32_bf16 v[20:23], v[210:213], v[206:209], v[174:177]
	v_mfma_f32_16x16x32_bf16 v[8:11], v[214:217], v[206:209], v[8:11]
	v_mfma_f32_16x16x32_bf16 v[4:7], v[210:213], v[238:241], v[4:7]
	v_mfma_f32_16x16x32_bf16 v[52:55], v[222:225], v[182:185], v[24:27]
	v_mfma_f32_16x16x32_bf16 v[24:27], v[218:221], v[234:237], v[20:23]
	v_mfma_f32_16x16x32_bf16 v[20:23], v[222:225], v[234:237], v[8:11]
	v_mfma_f32_16x16x32_bf16 v[8:11], v[218:221], v[242:245], v[4:7]
	v_mfma_f32_16x16x32_bf16 v[4:7], v[214:217], v[238:241], v[194:197]
	v_mfma_f32_16x16x32_bf16 v[4:7], v[222:225], v[242:245], v[4:7]
	s_setprio 0
	s_barrier
	s_and_saveexec_b64 s[68:69], s[2:3]
	s_cbranch_execz .LBB0_271
	s_barrier
	s_branch .LBB0_271

; #define STAGE(P, BASE, br, kt) do { const char* _gb = (const char*)(BASE) + ((size_t)(br) * K + (size_t)(kt) * BK) * 2; \
;     __builtin_amdgcn_global_load_lds((const unsigned*)(_gb + loff0), (unsigned*)((char*)(P) + tid * 16), 16, 0, 0); \
;     __builtin_amdgcn_global_load_lds((const unsigned*)(_gb + (size_t)K * 128 + loff0), (unsigned*)((char*)(P) + tid * 16 + 8192), 16, 0, 0); } while (0)
; #define BAR __builtin_amdgcn_s_barrier()
; template <int EPI> ...
;     ...
;   STAGE(SB(0, 0), Bt, bcol, 0); STAGE(SA(0, 0), A, brow, 0);
;   STAGE(SB(0, 1), Bt, bcol + HALF, 0); STAGE(SA(0, 1), A, brow + HALF, 0);
;   if (wr == 1) BAR;
; template <int EPI>
; __device__ __forceinline__ void gemm_phase(const u16* A, const u16* Bt, int M, int N, int K, u16* out, int ldo,
;                                            const float* aux, int bid, int nblk, int wv) {
;     ...
;   for (int base = 0; base < ntile; base += nblk) {
;     int wgid;
;     if (base + nblk <= ntile && (nblk & 7) == 0) wgid = base + (bid & 7) * (nblk >> 3) + (bid >> 3);
;     else wgid = base + bid;
;     if (wgid >= ntile) break;
;     int nig = WGM * nN, gid = wgid / nig, fm = gid * WGM, gsz = min(nM - fm, WGM);
;     int pm = fm + ((wgid % nig) % gsz), pn = (wgid % nig) / gsz;
;     int brow = pm * BM, bcol = pn * BM;
;     gemm_tile<EPI>(A, Bt, K, brow, bcol, out, ldo, EPI == 1 ? pn * HALF : bcol, aux, tid);
.LBB0_320:
	s_mov_b32 s62, s72
	s_add_i32 s72, s72, s33
	s_cmpk_lt_i32 s72, 0x401
	s_cselect_b64 s[60:61], -1, 0
	s_and_b64 s[60:61], s[44:45], s[60:61]
	s_and_b64 s[60:61], s[60:61], exec
	s_cselect_b32 s60, s86, s91
	s_add_i32 s62, s60, s62
	s_cmpk_gt_i32 s62, 0x3ff
	s_mov_b64 s[60:61], -1
	s_cbranch_scc1 .LBB0_319
	s_sub_i32 s62, 0x3ff, s62
	s_ashr_i32 s60, s62, 31
	s_lshr_b32 s60, s60, 26
	s_add_i32 s60, s62, s60
	s_and_b32 s61, s60, 0xffc0
	s_sub_i32 s61, s62, s61
	s_bfe_i32 s62, s61, 0x80000
	s_bfe_u32 s62, s62, 0x3000c
	s_add_i32 s62, s61, s62
	s_bfe_i32 s63, s62, 0x80000
	s_and_b32 s62, s62, 0xf8
	s_sub_i32 s61, s61, s62
	s_sext_i32_i16 s63, s63
	s_sext_i32_i8 s61, s61
	s_lshl_b32 s60, s60, 5
	s_ashr_i32 s64, s63, 3
	s_and_b32 s60, s60, 0xfffff800
	s_lshl_b32 s73, s61, 8
	s_add_i32 s73, s73, s60
	s_lshl_b32 s60, s64, 8
	s_mul_i32 s66, s64, 0x2c0000
	s_mul_hi_i32 s67, s60, 0x2c00
	s_add_u32 s62, s68, s66
	s_addc_u32 s63, s69, s67
	v_readfirstlane_b32 s61, v135
	s_mul_i32 s77, s73, 0x2c00
	v_lshl_add_u64 v[0:1], s[62:63], 0, v[128:129]
	s_mov_b32 m0, s61
	v_readfirstlane_b32 s61, v136
	s_mul_hi_i32 s76, s73, 0x2c00
	s_add_u32 s62, s14, s77
	global_load_lds_dwordx4 v[0:1], off
	v_lshl_add_u64 v[2:3], v[0:1], 0, s[8:9]
	s_mov_b32 m0, s61
	s_addc_u32 s63, s43, s76
	global_load_lds_dwordx4 v[2:3], off
	v_lshl_add_u64 v[2:3], s[62:63], 0, v[128:129]
	s_mul_i32 s62, s64, 0x160000
	v_readfirstlane_b32 s61, v137
	s_ashr_i32 s63, s62, 31
	s_mov_b32 m0, s61
	v_readfirstlane_b32 s61, v138
	s_lshl_b64 s[62:63], s[62:63], 1
	global_load_lds_dwordx4 v[2:3], off
	s_mov_b32 m0, s61
	s_add_u32 s61, s68, s62
	s_addc_u32 s65, s69, s63
	s_add_u32 s64, s61, 0x160000
	v_lshl_add_u64 v[4:5], v[2:3], 0, s[8:9]
	s_addc_u32 s65, s65, 0
	v_readfirstlane_b32 s61, v139
	global_load_lds_dwordx4 v[4:5], off
	v_lshl_add_u64 v[4:5], s[64:65], 0, v[128:129]
	s_mov_b32 m0, s61
	v_readfirstlane_b32 s61, v140
	global_load_lds_dwordx4 v[4:5], off
	s_mov_b32 m0, s61
	s_or_b32 s61, s73, 0x80
	s_mul_i32 s75, s61, 0x2c00
	s_mul_hi_i32 s74, s61, 0x2c00
	s_add_u32 s64, s14, s75
	v_lshl_add_u64 v[6:7], v[4:5], 0, s[8:9]
	s_addc_u32 s65, s43, s74
	v_readfirstlane_b32 s61, v141
	global_load_lds_dwordx4 v[6:7], off
	v_lshl_add_u64 v[6:7], s[64:65], 0, v[128:129]
	s_mov_b32 m0, s61
	v_readfirstlane_b32 s61, v142
	global_load_lds_dwordx4 v[6:7], off
	v_lshl_add_u64 v[6:7], v[6:7], 0, s[8:9]
	s_mov_b32 m0, s61
	s_nop 0
	global_load_lds_dwordx4 v[6:7], off
	s_and_saveexec_b64 s[64:65], s[4:5]
	s_cbranch_execz .LBB0_323
	s_barrier

; #define STAGE(P, BASE, br, kt) do { const char* _gb = (const char*)(BASE) + ((size_t)(br) * K + (size_t)(kt) * BK) * 2; \
;     __builtin_amdgcn_global_load_lds((const unsigned*)(_gb + loff0), (unsigned*)((char*)(P) + tid * 16), 16, 0, 0); \
;     __builtin_amdgcn_global_load_lds((const unsigned*)(_gb + (size_t)K * 128 + loff0), (unsigned*)((char*)(P) + tid * 16 + 8192), 16, 0, 0); } while (0)
; #define BAR __builtin_amdgcn_s_barrier()
; template <int EPI> ...
;     ...
;   STAGE(SB(0, 0), Bt, bcol, 0); STAGE(SA(0, 0), A, brow, 0);
;   STAGE(SB(0, 1), Bt, bcol + HALF, 0); STAGE(SA(0, 1), A, brow + HALF, 0);
;   if (wr == 1) BAR;
; template <int EPI>
; __device__ __forceinline__ void gemm_phase(const u16* A, const u16* Bt, int M, int N, int K, u16* out, int ldo,
;                                            const float* aux, int bid, int nblk, int wv) {
;     ...
;   for (int base = 0; base < ntile; base += nblk) {
;     int wgid;
;     if (base + nblk <= ntile && (nblk & 7) == 0) wgid = base + (bid & 7) * (nblk >> 3) + (bid >> 3);
;     else wgid = base + bid;
;     if (wgid >= ntile) break;
;     int nig = WGM * nN, gid = wgid / nig, fm = gid * WGM, gsz = min(nM - fm, WGM);
;     int pm = fm + ((wgid % nig) % gsz), pn = (wgid % nig) / gsz;
;     int brow = pm * BM, bcol = pn * BM;
;     gemm_tile<EPI>(A, Bt, K, brow, bcol, out, ldo, EPI == 1 ? pn * HALF : bcol, aux, tid);
.LBB0_1014:
	s_mov_b32 s60, s74
	s_add_i32 s74, s74, s33
	s_cmpk_lt_i32 s74, 0x401
	s_cselect_b64 s[58:59], -1, 0
	s_and_b64 s[58:59], s[44:45], s[58:59]
	s_and_b64 s[58:59], s[58:59], exec
	s_cselect_b32 s58, s86, s91
	s_add_i32 s60, s58, s60
	s_cmpk_gt_i32 s60, 0x3ff
	s_mov_b64 s[58:59], -1
	s_cbranch_scc1 .LBB0_1013
	s_sub_i32 s60, 0x3ff, s60
	s_ashr_i32 s58, s60, 31
	s_lshr_b32 s58, s58, 26
	s_add_i32 s58, s60, s58
	s_and_b32 s59, s58, 0xffc0
	s_sub_i32 s59, s60, s59
	s_bfe_i32 s60, s59, 0x80000
	s_bfe_u32 s60, s60, 0x3000c
	s_add_i32 s60, s59, s60
	s_bfe_i32 s61, s60, 0x80000
	s_and_b32 s60, s60, 0xf8
	s_sub_i32 s59, s59, s60
	s_sext_i32_i8 s59, s59
	s_lshl_b32 s58, s58, 5
	s_sext_i32_i16 s61, s61
	s_and_b32 s58, s58, 0xfffff800
	s_lshl_b32 s59, s59, 8
	s_add_i32 s58, s59, s58
	s_lshl_b32 s59, s61, 5
	s_and_b32 s60, s59, 0xffffff00
	s_ashr_i32 s61, s60, 31
	s_lshl_b64 s[64:65], s[60:61], 12
	s_add_u32 s62, s70, s64
	s_addc_u32 s63, s71, s65
	v_readfirstlane_b32 s59, v135
	v_lshl_add_u64 v[0:1], s[62:63], 0, v[128:129]
	s_mov_b32 m0, s59
	v_readfirstlane_b32 s59, v136
	global_load_lds_dwordx4 v[0:1], off
	s_mov_b32 m0, s59
	s_ashr_i32 s59, s58, 31
	s_lshl_b64 s[66:67], s[58:59], 12
	s_add_u32 s62, s14, s66
	v_lshl_add_u64 v[2:3], v[0:1], 0, s[8:9]
	s_addc_u32 s63, s43, s67
	global_load_lds_dwordx4 v[2:3], off
	v_lshl_add_u64 v[2:3], s[62:63], 0, v[128:129]
	s_or_b32 s62, s60, 0x80
	s_ashr_i32 s63, s62, 31
	v_readfirstlane_b32 s59, v137
	s_lshl_b64 s[62:63], s[62:63], 12
	s_mov_b32 m0, s59
	v_readfirstlane_b32 s59, v138
	s_add_u32 s62, s70, s62
	global_load_lds_dwordx4 v[2:3], off
	v_lshl_add_u64 v[4:5], v[2:3], 0, s[8:9]
	s_mov_b32 m0, s59
	s_addc_u32 s63, s71, s63
	global_load_lds_dwordx4 v[4:5], off
	v_lshl_add_u64 v[4:5], s[62:63], 0, v[128:129]
	s_or_b32 s62, s58, 0x80
	s_ashr_i32 s63, s62, 31
	v_readfirstlane_b32 s59, v139
	s_lshl_b64 s[62:63], s[62:63], 12
	s_mov_b32 m0, s59
	v_readfirstlane_b32 s59, v140
	s_add_u32 s68, s14, s62
	global_load_lds_dwordx4 v[4:5], off
	v_lshl_add_u64 v[6:7], v[4:5], 0, s[8:9]
	s_mov_b32 m0, s59
	s_addc_u32 s69, s43, s63
	v_readfirstlane_b32 s59, v141
	global_load_lds_dwordx4 v[6:7], off
	v_lshl_add_u64 v[6:7], s[68:69], 0, v[128:129]
	s_mov_b32 m0, s59
	v_readfirstlane_b32 s59, v142
	global_load_lds_dwordx4 v[6:7], off
	v_lshl_add_u64 v[6:7], v[6:7], 0, s[8:9]
	s_mov_b32 m0, s59
	s_nop 0
	global_load_lds_dwordx4 v[6:7], off
	s_and_saveexec_b64 s[68:69], s[4:5]
	s_cbranch_execz .LBB0_1017
	s_barrier

; #define STAGE(P, BASE, br, kt) do { const char* _gb = (const char*)(BASE) + ((size_t)(br) * K + (size_t)(kt) * BK) * 2; \
;     __builtin_amdgcn_global_load_lds((const unsigned*)(_gb + loff0), (unsigned*)((char*)(P) + tid * 16), 16, 0, 0); \
;     __builtin_amdgcn_global_load_lds((const unsigned*)(_gb + (size_t)K * 128 + loff0), (unsigned*)((char*)(P) + tid * 16 + 8192), 16, 0, 0); } while (0)
; #define BAR __builtin_amdgcn_s_barrier()
; template <int EPI> ...
;     ...
;   STAGE(SB(0, 0), Bt, bcol, 0); STAGE(SA(0, 0), A, brow, 0);
;   STAGE(SB(0, 1), Bt, bcol + HALF, 0); STAGE(SA(0, 1), A, brow + HALF, 0);
;   if (wr == 1) BAR;
; template <int EPI>
; __device__ __forceinline__ void gemm_phase(const u16* A, const u16* Bt, int M, int N, int K, u16* out, int ldo,
;                                            const float* aux, int bid, int nblk, int wv) {
;     ...
;   for (int base = 0; base < ntile; base += nblk) {
;     int wgid;
;     if (base + nblk <= ntile && (nblk & 7) == 0) wgid = base + (bid & 7) * (nblk >> 3) + (bid >> 3);
;     else wgid = base + bid;
;     if (wgid >= ntile) break;
;     int nig = WGM * nN, gid = wgid / nig, fm = gid * WGM, gsz = min(nM - fm, WGM);
;     int pm = fm + ((wgid % nig) % gsz), pn = (wgid % nig) / gsz;
;     int brow = pm * BM, bcol = pn * BM;
;     gemm_tile<EPI>(A, Bt, K, brow, bcol, out, ldo, EPI == 1 ? pn * HALF : bcol, aux, tid);
.LBB0_1148:
	s_mov_b32 s60, s70
	s_add_i32 s70, s70, s33
	s_cmpk_lt_i32 s70, 0x401
	s_cselect_b64 s[58:59], -1, 0
	s_and_b64 s[58:59], s[44:45], s[58:59]
	s_and_b64 s[58:59], s[58:59], exec
	s_cselect_b32 s58, s86, s91
	s_add_i32 s60, s58, s60
	s_cmpk_gt_i32 s60, 0x3ff
	s_mov_b64 s[58:59], -1
	s_cbranch_scc1 .LBB0_1147
	s_sub_i32 s60, 0x3ff, s60
	s_ashr_i32 s58, s60, 31
	s_lshr_b32 s58, s58, 26
	s_add_i32 s58, s60, s58
	s_and_b32 s59, s58, 0xffc0
	s_sub_i32 s59, s60, s59
	s_bfe_i32 s60, s59, 0x80000
	s_bfe_u32 s60, s60, 0x3000c
	s_add_i32 s60, s59, s60
	s_bfe_i32 s61, s60, 0x80000
	s_and_b32 s60, s60, 0xf8
	s_sub_i32 s59, s59, s60
	s_sext_i32_i16 s61, s61
	s_sext_i32_i8 s59, s59
	s_lshl_b32 s58, s58, 5
	s_ashr_i32 s62, s61, 3
	s_and_b32 s58, s58, 0xfffff800
	s_lshl_b32 s71, s59, 8
	s_add_i32 s71, s71, s58
	s_lshl_b32 s58, s62, 8
	s_mul_i32 s64, s62, 0x2c0000
	s_mul_hi_i32 s65, s58, 0x2c00
	s_add_u32 s60, s66, s64
	s_addc_u32 s61, s67, s65
	v_readfirstlane_b32 s59, v135
	s_mul_i32 s75, s71, 0x2c00
	v_lshl_add_u64 v[0:1], s[60:61], 0, v[128:129]
	s_mov_b32 m0, s59
	v_readfirstlane_b32 s59, v136
	s_mul_hi_i32 s74, s71, 0x2c00
	s_add_u32 s60, s14, s75
	global_load_lds_dwordx4 v[0:1], off
	v_lshl_add_u64 v[2:3], v[0:1], 0, s[8:9]
	s_mov_b32 m0, s59
	s_addc_u32 s61, s43, s74
	global_load_lds_dwordx4 v[2:3], off
	v_lshl_add_u64 v[2:3], s[60:61], 0, v[128:129]
	s_mul_i32 s60, s62, 0x160000
	v_readfirstlane_b32 s59, v137
	s_ashr_i32 s61, s60, 31
	s_mov_b32 m0, s59
	v_readfirstlane_b32 s59, v138
	s_lshl_b64 s[60:61], s[60:61], 1
	global_load_lds_dwordx4 v[2:3], off
	s_mov_b32 m0, s59
	s_add_u32 s59, s66, s60
	s_addc_u32 s63, s67, s61
	s_add_u32 s62, s59, 0x160000
	v_lshl_add_u64 v[4:5], v[2:3], 0, s[8:9]
	s_addc_u32 s63, s63, 0
	v_readfirstlane_b32 s59, v139
	global_load_lds_dwordx4 v[4:5], off
	v_lshl_add_u64 v[4:5], s[62:63], 0, v[128:129]
	s_mov_b32 m0, s59
	v_readfirstlane_b32 s59, v140
	global_load_lds_dwordx4 v[4:5], off
	s_mov_b32 m0, s59
	s_or_b32 s59, s71, 0x80
	s_mul_i32 s73, s59, 0x2c00
	s_mul_hi_i32 s72, s59, 0x2c00
	s_add_u32 s62, s14, s73
	v_lshl_add_u64 v[6:7], v[4:5], 0, s[8:9]
	s_addc_u32 s63, s43, s72
	v_readfirstlane_b32 s59, v141
	global_load_lds_dwordx4 v[6:7], off
	v_lshl_add_u64 v[6:7], s[62:63], 0, v[128:129]
	s_mov_b32 m0, s59
	v_readfirstlane_b32 s59, v142
	global_load_lds_dwordx4 v[6:7], off
	v_lshl_add_u64 v[6:7], v[6:7], 0, s[8:9]
	s_mov_b32 m0, s59
	s_nop 0
	global_load_lds_dwordx4 v[6:7], off
	s_and_saveexec_b64 s[62:63], s[4:5]
	s_cbranch_execz .LBB0_1151
	s_barrier

; __global__ void __launch_bounds__(512) fwd_megakernel(Params p_unused) {
	.amdhsa_kernel _Z14fwd_megakernel6Params
		.amdhsa_group_segment_fixed_size 0
		.amdhsa_private_segment_fixed_size 0
		.amdhsa_kernarg_size 488
		.amdhsa_user_sgpr_count 2
		.amdhsa_user_sgpr_dispatch_ptr 0
		.amdhsa_user_sgpr_queue_ptr 0
		.amdhsa_user_sgpr_kernarg_segment_ptr 1
		.amdhsa_user_sgpr_dispatch_id 0
		.amdhsa_user_sgpr_kernarg_preload_length 0
		.amdhsa_user_sgpr_kernarg_preload_offset 0
		.amdhsa_user_sgpr_private_segment_size 0
		.amdhsa_uses_dynamic_stack 0
		.amdhsa_enable_private_segment 0
		.amdhsa_system_sgpr_workgroup_id_x 1
		.amdhsa_system_sgpr_workgroup_id_y 0
		.amdhsa_system_sgpr_workgroup_id_z 0
		.amdhsa_system_sgpr_workgroup_info 0
		.amdhsa_system_vgpr_workitem_id 2
		.amdhsa_next_free_vgpr 256
		.amdhsa_next_free_sgpr 98
		.amdhsa_accum_offset 256
		.amdhsa_reserve_vcc 1
		.amdhsa_float_round_mode_32 0
		.amdhsa_float_round_mode_16_64 0
		.amdhsa_float_denorm_mode_32 3
		.amdhsa_float_denorm_mode_16_64 3
		.amdhsa_dx10_clamp 1
		.amdhsa_ieee_mode 1
		.amdhsa_fp16_overflow 0
		.amdhsa_tg_split 0
		.amdhsa_exception_fp_ieee_invalid_op 0
		.amdhsa_exception_fp_denorm_src 0
		.amdhsa_exception_fp_ieee_div_zero 0
		.amdhsa_exception_fp_ieee_overflow 0
		.amdhsa_exception_fp_ieee_underflow 0
		.amdhsa_exception_fp_ieee_inexact 0
		.amdhsa_exception_int_div_zero 0
	.end_amdhsa_kernel

; __global__ void __launch_bounds__(512) fwd_megakernel(Params p_unused) {
amdhsa.kernels:
  - .agpr_count:     0
    .args:
      - .offset:         0
        .size:           232
        .value_kind:     by_value
      - .offset:         232
        .size:           4
        .value_kind:     hidden_block_count_x
      - .offset:         236
        .size:           4
        .value_kind:     hidden_block_count_y
      - .offset:         240
        .size:           4
        .value_kind:     hidden_block_count_z
      - .offset:         244
        .size:           2
        .value_kind:     hidden_group_size_x
      - .offset:         246
        .size:           2
        .value_kind:     hidden_group_size_y
      - .offset:         248
        .size:           2
        .value_kind:     hidden_group_size_z
      - .offset:         250
        .size:           2
        .value_kind:     hidden_remainder_x
      - .offset:         252
        .size:           2
        .value_kind:     hidden_remainder_y
      - .offset:         254
        .size:           2
        .value_kind:     hidden_remainder_z
      - .offset:         272
        .size:           8
        .value_kind:     hidden_global_offset_x
      - .offset:         280
        .size:           8
        .value_kind:     hidden_global_offset_y
      - .offset:         288
        .size:           8
        .value_kind:     hidden_global_offset_z
      - .offset:         296
        .size:           2
        .value_kind:     hidden_grid_dims
      - .offset:         320
        .size:           8
        .value_kind:     hidden_multigrid_sync_arg
      - .offset:         352
        .size:           4
        .value_kind:     hidden_dynamic_lds_size
    .group_segment_fixed_size: 0
    .kernarg_segment_align: 8
    .kernarg_segment_size: 488
    .language:       OpenCL C
    .language_version:
      - 2
      - 0
    .max_flat_workgroup_size: 512
    .name:           _Z14fwd_megakernel6Params
    .private_segment_fixed_size: 0
    .sgpr_count:     104
    .sgpr_spill_count: 1
    .symbol:         _Z14fwd_megakernel6Params.kd
    .uniform_work_group_size: 1
    .uses_dynamic_stack: false
    .vgpr_count:     256
    .vgpr_spill_count: 0
    .wavefront_size: 64
